# attention: the next query's q fragments are requested in the last sub-block (after its QK) instead of at the query top
# speedup vs baseline: 1.0033x; 1.0033x over previous
.LBB0_135:
	s_and_b32 s0, s76, 0x7ffff000
	s_mov_b32 s1, s77
	s_lshl_b64 s[0:1], s[0:1], 9
	v_mov_b32_e32 v72, 0
	s_and_b32 s29, s76, 0xfff
	v_mad_u64_u32 v[106:107], s[2:3], s76, v188, v[100:101]
	v_lshl_add_u64 v[108:109], v[102:103], 0, s[0:1]
	v_mov_b32_e32 v128, 0xff800000
	s_cmp_lg_u32 s25, 1
	s_cbranch_scc1 .Latt_skipq
	global_load_dwordx4 v[196:199], v[106:107], off
	global_load_dwordx4 v[200:203], v[106:107], off offset:64
	global_load_dwordx4 v[204:207], v[106:107], off offset:128
	global_load_dwordx4 v[208:211], v[106:107], off offset:192
	global_load_dwordx4 v[212:215], v[106:107], off offset:256
	global_load_dwordx4 v[216:219], v[106:107], off offset:320
	global_load_dwordx4 v[220:223], v[106:107], off offset:384
	global_load_dwordx4 v[224:227], v[106:107], off offset:448
.Latt_skipq:
	s_mov_b32 s30, 0
	v_mov_b32_e32 v68, 0
	v_mov_b32_e32 v69, v72
	v_mov_b32_e32 v70, v72
	v_mov_b32_e32 v71, v72
	v_mov_b32_e32 v24, 0
	v_mov_b32_e32 v25, v72
	v_mov_b32_e32 v26, v72
	v_mov_b32_e32 v27, v72
	v_mov_b32_e32 v64, 0
	v_mov_b32_e32 v65, v72
	v_mov_b32_e32 v66, v72
	v_mov_b32_e32 v67, v72
	v_mov_b32_e32 v60, 0
	v_mov_b32_e32 v61, v72
	v_mov_b32_e32 v62, v72
	v_mov_b32_e32 v63, v72
	v_mov_b32_e32 v56, 0
	v_mov_b32_e32 v57, v72
	v_mov_b32_e32 v58, v72
	v_mov_b32_e32 v59, v72
	v_mov_b32_e32 v52, 0
	v_mov_b32_e32 v53, v72
	v_mov_b32_e32 v54, v72
	v_mov_b32_e32 v55, v72
	v_mov_b32_e32 v48, 0
	v_mov_b32_e32 v49, v72
	v_mov_b32_e32 v50, v72
	v_mov_b32_e32 v51, v72
	v_mov_b32_e32 v44, 0
	v_mov_b32_e32 v45, v72
	v_mov_b32_e32 v46, v72
	v_mov_b32_e32 v47, v72
	v_mov_b32_e32 v40, 0
	v_mov_b32_e32 v41, v72
	v_mov_b32_e32 v42, v72
	v_mov_b32_e32 v43, v72
	v_mov_b32_e32 v28, 0
	v_mov_b32_e32 v29, v72
	v_mov_b32_e32 v30, v72
	v_mov_b32_e32 v31, v72
	v_mov_b32_e32 v20, 0
	v_mov_b32_e32 v21, v72
	v_mov_b32_e32 v22, v72
	v_mov_b32_e32 v23, v72
	v_mov_b32_e32 v16, 0
	v_mov_b32_e32 v17, v72
	v_mov_b32_e32 v18, v72
	v_mov_b32_e32 v19, v72
	v_mov_b32_e32 v12, 0
	v_mov_b32_e32 v13, v72
	v_mov_b32_e32 v14, v72
	v_mov_b32_e32 v15, v72
	v_mov_b32_e32 v8, 0
	v_mov_b32_e32 v9, v72
	v_mov_b32_e32 v10, v72
	v_mov_b32_e32 v11, v72
	v_mov_b32_e32 v4, 0
	v_mov_b32_e32 v5, v72
	v_mov_b32_e32 v6, v72
	v_mov_b32_e32 v7, v72
	v_mov_b32_e32 v0, 0
	v_mov_b32_e32 v1, v72
	v_mov_b32_e32 v2, v72
	v_mov_b32_e32 v3, v72
	v_and_b32_e32 v132, 63, v165
	v_and_b32_e32 v133, 15, v132
	v_lshrrev_b32_e32 v134, 4, v132
	v_and_b32_e32 v135, 7, v133
	v_lshlrev_b32_e32 v135, 1, v135
	s_lshl_b32 s0, s22, 14
	v_lshl_add_u32 v136, v133, 9, s0
	v_add_u32_e32 v137, 0, v134
	v_xor_b32_e32 v137, v137, v135
	v_lshl_add_u32 v88, v137, 4, v136
	v_add_u32_e32 v137, 4, v134
	v_xor_b32_e32 v137, v137, v135
	v_lshl_add_u32 v89, v137, 4, v136
	v_add_u32_e32 v137, 8, v134
	v_xor_b32_e32 v137, v137, v135
	v_lshl_add_u32 v90, v137, 4, v136
	v_add_u32_e32 v137, 12, v134
	v_xor_b32_e32 v137, v137, v135
	v_lshl_add_u32 v91, v137, 4, v136
	v_lshrrev_b32_e32 v137, 2, v133
	v_lshl_add_u32 v137, v134, 2, v137
	v_and_b32_e32 v138, 7, v137
	v_lshl_add_u32 v139, v137, 9, s0
	v_bfe_u32 v140, v133, 1, 1
	v_and_b32_e32 v141, 1, v133
	v_lshl_add_u32 v139, v141, 3, v139
	v_lshl_add_u32 v139, v140, 4, v139
	v_xor_b32_e32 v137, 0, v138
	v_lshl_add_u32 v92, v137, 5, v139
	v_xor_b32_e32 v137, 1, v138
	v_lshl_add_u32 v93, v137, 5, v139
	v_xor_b32_e32 v137, 2, v138
	v_lshl_add_u32 v94, v137, 5, v139
	v_xor_b32_e32 v137, 3, v138
	v_lshl_add_u32 v95, v137, 5, v139
	v_xor_b32_e32 v137, 4, v138
	v_lshl_add_u32 v96, v137, 5, v139
	v_xor_b32_e32 v137, 5, v138
	v_lshl_add_u32 v97, v137, 5, v139
	v_xor_b32_e32 v137, 6, v138
	v_lshl_add_u32 v98, v137, 5, v139
	v_xor_b32_e32 v137, 7, v138
	v_lshl_add_u32 v99, v137, 5, v139
	v_and_b32_e32 v137, 31, v132
	v_add_u32_e32 v138, 0, v115
	v_and_b32_e32 v138, 7, v138
	v_lshlrev_b32_e32 v138, 1, v138
	v_xor_b32_e32 v138, v138, v137
	v_lshlrev_b32_e32 v152, 4, v138
	v_add_u32_e32 v138, 2, v115
	v_and_b32_e32 v138, 7, v138
	v_lshlrev_b32_e32 v138, 1, v138
	v_xor_b32_e32 v138, v138, v137
	v_lshlrev_b32_e32 v153, 4, v138
	v_add_u32_e32 v138, 4, v115
	v_and_b32_e32 v138, 7, v138
	v_lshlrev_b32_e32 v138, 1, v138
	v_xor_b32_e32 v138, v138, v137
	v_lshlrev_b32_e32 v154, 4, v138
	v_add_u32_e32 v138, 6, v115
	v_and_b32_e32 v138, 7, v138
	v_lshlrev_b32_e32 v138, 1, v138
	v_xor_b32_e32 v138, v138, v137
	v_lshlrev_b32_e32 v155, 4, v138
	v_mov_b32_e32 v244, v124
	s_nop 1
	v_readlane_b32 s0, v244, 0
	v_readlane_b32 s1, v244, 1
	v_readlane_b32 vcc_lo, v244, 2
	v_readlane_b32 vcc_hi, v244, 3
	s_mov_b32 exec_lo, 0xffff
	s_mov_b32 exec_hi, 0x0
	v_mov_b32_e32 v164, s0
	v_mov_b32_e32 v166, s1
	v_mov_b32_e32 v168, vcc_lo
	v_mov_b32_e32 v169, vcc_hi
	s_mov_b64 exec, -1
	s_max_i32 s0, s0, 0
	s_max_i32 s1, s1, 0
	s_max_i32 vcc_lo, vcc_lo, 0
	s_max_i32 vcc_hi, vcc_hi, 0
	s_sub_i32 s1, s1, s0
	s_sub_i32 vcc_hi, vcc_hi, vcc_lo
	s_lshl_b32 s0, s0, 9
	s_lshl_b32 s1, s1, 9
	s_lshl_b32 vcc_lo, vcc_lo, 9
	s_lshl_b32 vcc_hi, vcc_hi, 9
	v_add_u32_e32 v156, s0, v152
	v_add_u32_e32 v157, vcc_lo, v153
	v_mad_i32_i24 v156, v115, s1, v156
	v_mad_i32_i24 v157, v115, vcc_hi, v157
	v_readlane_b32 s0, v244, 4
	v_readlane_b32 s1, v244, 5
	v_readlane_b32 vcc_lo, v244, 6
	v_readlane_b32 vcc_hi, v244, 7
	s_mov_b32 exec_lo, 0xffff0000
	s_mov_b32 exec_hi, 0x0
	v_mov_b32_e32 v164, s0
	v_mov_b32_e32 v166, s1
	v_mov_b32_e32 v168, vcc_lo
	v_mov_b32_e32 v169, vcc_hi
	s_mov_b64 exec, -1
	s_max_i32 s0, s0, 0
	s_max_i32 s1, s1, 0
	s_max_i32 vcc_lo, vcc_lo, 0
	s_max_i32 vcc_hi, vcc_hi, 0
	s_sub_i32 s1, s1, s0
	s_sub_i32 vcc_hi, vcc_hi, vcc_lo
	s_lshl_b32 s0, s0, 9
	s_lshl_b32 s1, s1, 9
	s_lshl_b32 vcc_lo, vcc_lo, 9
	s_lshl_b32 vcc_hi, vcc_hi, 9
	v_add_u32_e32 v158, s0, v154
	v_add_u32_e32 v159, vcc_lo, v155
	v_mad_i32_i24 v158, v115, s1, v158
	v_mad_i32_i24 v159, v115, vcc_hi, v159
	v_readlane_b32 s0, v244, 8
	v_readlane_b32 s1, v244, 9
	v_readlane_b32 vcc_lo, v244, 10
	v_readlane_b32 vcc_hi, v244, 11
	s_mov_b32 exec_lo, 0x0
	s_mov_b32 exec_hi, 0xffff
	v_mov_b32_e32 v164, s0
	v_mov_b32_e32 v166, s1
	v_mov_b32_e32 v168, vcc_lo
	v_mov_b32_e32 v169, vcc_hi
	s_mov_b64 exec, -1
	s_max_i32 s0, s0, 0
	s_max_i32 s1, s1, 0
	s_max_i32 vcc_lo, vcc_lo, 0
	s_max_i32 vcc_hi, vcc_hi, 0
	s_sub_i32 s1, s1, s0
	s_sub_i32 vcc_hi, vcc_hi, vcc_lo
	s_lshl_b32 s0, s0, 9
	s_lshl_b32 s1, s1, 9
	s_lshl_b32 vcc_lo, vcc_lo, 9
	s_lshl_b32 vcc_hi, vcc_hi, 9
	v_add_u32_e32 v160, s0, v152
	v_add_u32_e32 v161, vcc_lo, v153
	v_mad_i32_i24 v160, v115, s1, v160
	v_mad_i32_i24 v161, v115, vcc_hi, v161
	v_readlane_b32 s0, v244, 12
	v_readlane_b32 s1, v244, 13
	v_readlane_b32 vcc_lo, v244, 14
	v_readlane_b32 vcc_hi, v244, 15
	s_mov_b32 exec_lo, 0x0
	s_mov_b32 exec_hi, 0xffff0000
	v_mov_b32_e32 v164, s0
	v_mov_b32_e32 v166, s1
	v_mov_b32_e32 v168, vcc_lo
	v_mov_b32_e32 v169, vcc_hi
	s_mov_b64 exec, -1
	s_max_i32 s0, s0, 0
	s_max_i32 s1, s1, 0
	s_max_i32 vcc_lo, vcc_lo, 0
	s_max_i32 vcc_hi, vcc_hi, 0
	s_sub_i32 s1, s1, s0
	s_sub_i32 vcc_hi, vcc_hi, vcc_lo
	s_lshl_b32 s0, s0, 9
	s_lshl_b32 s1, s1, 9
	s_lshl_b32 vcc_lo, vcc_lo, 9
	s_lshl_b32 vcc_hi, vcc_hi, 9
	v_add_u32_e32 v162, s0, v154
	v_add_u32_e32 v163, vcc_lo, v155
	v_mad_i32_i24 v162, v115, s1, v162
	v_mad_i32_i24 v163, v115, vcc_hi, v163
	v_readlane_b32 s0, v244, 16
	v_readlane_b32 s1, v244, 17
	v_readlane_b32 vcc_lo, v244, 18
	v_readlane_b32 vcc_hi, v244, 19
	s_mov_b32 exec_lo, 0xffff
	s_mov_b32 exec_hi, 0x0
	v_mov_b32_e32 v170, s0
	v_mov_b32_e32 v176, s1
	v_mov_b32_e32 v177, vcc_lo
	v_mov_b32_e32 v191, vcc_hi
	s_mov_b64 exec, -1
	s_max_i32 s0, s0, 0
	s_max_i32 s1, s1, 0
	s_max_i32 vcc_lo, vcc_lo, 0
	s_max_i32 vcc_hi, vcc_hi, 0
	s_sub_i32 s1, s1, s0
	s_sub_i32 vcc_hi, vcc_hi, vcc_lo
	s_lshl_b32 s0, s0, 9
	s_lshl_b32 s1, s1, 9
	s_lshl_b32 vcc_lo, vcc_lo, 9
	s_lshl_b32 vcc_hi, vcc_hi, 9
	v_add_u32_e32 v144, s0, v152
	v_add_u32_e32 v145, vcc_lo, v153
	v_mad_i32_i24 v144, v115, s1, v144
	v_mad_i32_i24 v145, v115, vcc_hi, v145
	v_readlane_b32 s0, v244, 20
	v_readlane_b32 s1, v244, 21
	v_readlane_b32 vcc_lo, v244, 22
	v_readlane_b32 vcc_hi, v244, 23
	s_mov_b32 exec_lo, 0xffff0000
	s_mov_b32 exec_hi, 0x0
	v_mov_b32_e32 v170, s0
	v_mov_b32_e32 v176, s1
	v_mov_b32_e32 v177, vcc_lo
	v_mov_b32_e32 v191, vcc_hi
	s_mov_b64 exec, -1
	s_max_i32 s0, s0, 0
	s_max_i32 s1, s1, 0
	s_max_i32 vcc_lo, vcc_lo, 0
	s_max_i32 vcc_hi, vcc_hi, 0
	s_sub_i32 s1, s1, s0
	s_sub_i32 vcc_hi, vcc_hi, vcc_lo
	s_lshl_b32 s0, s0, 9
	s_lshl_b32 s1, s1, 9
	s_lshl_b32 vcc_lo, vcc_lo, 9
	s_lshl_b32 vcc_hi, vcc_hi, 9
	v_add_u32_e32 v146, s0, v154
	v_add_u32_e32 v147, vcc_lo, v155
	v_mad_i32_i24 v146, v115, s1, v146
	v_mad_i32_i24 v147, v115, vcc_hi, v147
	v_readlane_b32 s0, v244, 24
	v_readlane_b32 s1, v244, 25
	v_readlane_b32 vcc_lo, v244, 26
	v_readlane_b32 vcc_hi, v244, 27
	s_mov_b32 exec_lo, 0x0
	s_mov_b32 exec_hi, 0xffff
	v_mov_b32_e32 v170, s0
	v_mov_b32_e32 v176, s1
	v_mov_b32_e32 v177, vcc_lo
	v_mov_b32_e32 v191, vcc_hi
	s_mov_b64 exec, -1
	s_max_i32 s0, s0, 0
	s_max_i32 s1, s1, 0
	s_max_i32 vcc_lo, vcc_lo, 0
	s_max_i32 vcc_hi, vcc_hi, 0
	s_sub_i32 s1, s1, s0
	s_sub_i32 vcc_hi, vcc_hi, vcc_lo
	s_lshl_b32 s0, s0, 9
	s_lshl_b32 s1, s1, 9
	s_lshl_b32 vcc_lo, vcc_lo, 9
	s_lshl_b32 vcc_hi, vcc_hi, 9
	v_add_u32_e32 v172, s0, v152
	v_add_u32_e32 v173, vcc_lo, v153
	v_mad_i32_i24 v172, v115, s1, v172
	v_mad_i32_i24 v173, v115, vcc_hi, v173
	v_readlane_b32 s0, v244, 28
	v_readlane_b32 s1, v244, 29
	v_readlane_b32 vcc_lo, v244, 30
	v_readlane_b32 vcc_hi, v244, 31
	s_mov_b32 exec_lo, 0x0
	s_mov_b32 exec_hi, 0xffff0000
	v_mov_b32_e32 v170, s0
	v_mov_b32_e32 v176, s1
	v_mov_b32_e32 v177, vcc_lo
	v_mov_b32_e32 v191, vcc_hi
	s_mov_b64 exec, -1
	s_max_i32 s0, s0, 0
	s_max_i32 s1, s1, 0
	s_max_i32 vcc_lo, vcc_lo, 0
	s_max_i32 vcc_hi, vcc_hi, 0
	s_sub_i32 s1, s1, s0
	s_sub_i32 vcc_hi, vcc_hi, vcc_lo
	s_lshl_b32 s0, s0, 9
	s_lshl_b32 s1, s1, 9
	s_lshl_b32 vcc_lo, vcc_lo, 9
	s_lshl_b32 vcc_hi, vcc_hi, 9
	v_add_u32_e32 v174, s0, v154
	v_add_u32_e32 v175, vcc_lo, v155
	v_mad_i32_i24 v174, v115, s1, v174
	v_mad_i32_i24 v175, v115, vcc_hi, v175

.Latt_a_odd:
	v_readlane_b32 s0, v244, 32
	v_readlane_b32 s1, v244, 33
	v_readlane_b32 vcc_lo, v244, 34
	v_readlane_b32 vcc_hi, v244, 35
	s_mov_b32 exec_lo, 0xffff
	s_mov_b32 exec_hi, 0x0
	v_mov_b32_e32 v164, s0
	v_mov_b32_e32 v166, s1
	v_mov_b32_e32 v168, vcc_lo
	v_mov_b32_e32 v169, vcc_hi
	s_mov_b64 exec, -1
	s_max_i32 s0, s0, 0
	s_max_i32 s1, s1, 0
	s_max_i32 vcc_lo, vcc_lo, 0
	s_max_i32 vcc_hi, vcc_hi, 0
	s_sub_i32 s1, s1, s0
	s_sub_i32 vcc_hi, vcc_hi, vcc_lo
	s_lshl_b32 s0, s0, 9
	s_lshl_b32 s1, s1, 9
	s_lshl_b32 vcc_lo, vcc_lo, 9
	s_lshl_b32 vcc_hi, vcc_hi, 9
	v_add_u32_e32 v156, s0, v152
	v_add_u32_e32 v157, vcc_lo, v153
	v_mad_i32_i24 v156, v115, s1, v156
	v_mad_i32_i24 v157, v115, vcc_hi, v157
	v_readlane_b32 s0, v244, 36
	v_readlane_b32 s1, v244, 37
	v_readlane_b32 vcc_lo, v244, 38
	v_readlane_b32 vcc_hi, v244, 39
	s_mov_b32 exec_lo, 0xffff0000
	s_mov_b32 exec_hi, 0x0
	v_mov_b32_e32 v164, s0
	v_mov_b32_e32 v166, s1
	v_mov_b32_e32 v168, vcc_lo
	v_mov_b32_e32 v169, vcc_hi
	s_mov_b64 exec, -1
	s_max_i32 s0, s0, 0
	s_max_i32 s1, s1, 0
	s_max_i32 vcc_lo, vcc_lo, 0
	s_max_i32 vcc_hi, vcc_hi, 0
	s_sub_i32 s1, s1, s0
	s_sub_i32 vcc_hi, vcc_hi, vcc_lo
	s_lshl_b32 s0, s0, 9
	s_lshl_b32 s1, s1, 9
	s_lshl_b32 vcc_lo, vcc_lo, 9
	s_lshl_b32 vcc_hi, vcc_hi, 9
	v_add_u32_e32 v158, s0, v154
	v_add_u32_e32 v159, vcc_lo, v155
	v_mad_i32_i24 v158, v115, s1, v158
	v_mad_i32_i24 v159, v115, vcc_hi, v159
	v_readlane_b32 s0, v244, 40
	v_readlane_b32 s1, v244, 41
	v_readlane_b32 vcc_lo, v244, 42
	v_readlane_b32 vcc_hi, v244, 43
	s_mov_b32 exec_lo, 0x0
	s_mov_b32 exec_hi, 0xffff
	v_mov_b32_e32 v164, s0
	v_mov_b32_e32 v166, s1
	v_mov_b32_e32 v168, vcc_lo
	v_mov_b32_e32 v169, vcc_hi
	s_mov_b64 exec, -1
	s_max_i32 s0, s0, 0
	s_max_i32 s1, s1, 0
	s_max_i32 vcc_lo, vcc_lo, 0
	s_max_i32 vcc_hi, vcc_hi, 0
	s_sub_i32 s1, s1, s0
	s_sub_i32 vcc_hi, vcc_hi, vcc_lo
	s_lshl_b32 s0, s0, 9
	s_lshl_b32 s1, s1, 9
	s_lshl_b32 vcc_lo, vcc_lo, 9
	s_lshl_b32 vcc_hi, vcc_hi, 9
	v_add_u32_e32 v160, s0, v152
	v_add_u32_e32 v161, vcc_lo, v153
	v_mad_i32_i24 v160, v115, s1, v160
	v_mad_i32_i24 v161, v115, vcc_hi, v161
	v_readlane_b32 s0, v244, 44
	v_readlane_b32 s1, v244, 45
	v_readlane_b32 vcc_lo, v244, 46
	v_readlane_b32 vcc_hi, v244, 47
	s_mov_b32 exec_lo, 0x0
	s_mov_b32 exec_hi, 0xffff0000
	v_mov_b32_e32 v164, s0
	v_mov_b32_e32 v166, s1
	v_mov_b32_e32 v168, vcc_lo
	v_mov_b32_e32 v169, vcc_hi
	s_mov_b64 exec, -1
	s_max_i32 s0, s0, 0
	s_max_i32 s1, s1, 0
	s_max_i32 vcc_lo, vcc_lo, 0
	s_max_i32 vcc_hi, vcc_hi, 0
	s_sub_i32 s1, s1, s0
	s_sub_i32 vcc_hi, vcc_hi, vcc_lo
	s_lshl_b32 s0, s0, 9
	s_lshl_b32 s1, s1, 9
	s_lshl_b32 vcc_lo, vcc_lo, 9
	s_lshl_b32 vcc_hi, vcc_hi, 9
	v_add_u32_e32 v162, s0, v154
	v_add_u32_e32 v163, vcc_lo, v155
	v_mad_i32_i24 v162, v115, s1, v162
	v_mad_i32_i24 v163, v115, vcc_hi, v163
	v_readlane_b32 s0, v244, 48
	v_readlane_b32 s1, v244, 49
	v_readlane_b32 vcc_lo, v244, 50
	v_readlane_b32 vcc_hi, v244, 51
	s_mov_b32 exec_lo, 0xffff
	s_mov_b32 exec_hi, 0x0
	v_mov_b32_e32 v170, s0
	v_mov_b32_e32 v176, s1
	v_mov_b32_e32 v177, vcc_lo
	v_mov_b32_e32 v191, vcc_hi
	s_mov_b64 exec, -1
	s_max_i32 s0, s0, 0
	s_max_i32 s1, s1, 0
	s_max_i32 vcc_lo, vcc_lo, 0
	s_max_i32 vcc_hi, vcc_hi, 0
	s_sub_i32 s1, s1, s0
	s_sub_i32 vcc_hi, vcc_hi, vcc_lo
	s_lshl_b32 s0, s0, 9
	s_lshl_b32 s1, s1, 9
	s_lshl_b32 vcc_lo, vcc_lo, 9
	s_lshl_b32 vcc_hi, vcc_hi, 9
	v_add_u32_e32 v144, s0, v152
	v_add_u32_e32 v145, vcc_lo, v153
	v_mad_i32_i24 v144, v115, s1, v144
	v_mad_i32_i24 v145, v115, vcc_hi, v145
	v_readlane_b32 s0, v244, 52
	v_readlane_b32 s1, v244, 53
	v_readlane_b32 vcc_lo, v244, 54
	v_readlane_b32 vcc_hi, v244, 55
	s_mov_b32 exec_lo, 0xffff0000
	s_mov_b32 exec_hi, 0x0
	v_mov_b32_e32 v170, s0
	v_mov_b32_e32 v176, s1
	v_mov_b32_e32 v177, vcc_lo
	v_mov_b32_e32 v191, vcc_hi
	s_mov_b64 exec, -1
	s_max_i32 s0, s0, 0
	s_max_i32 s1, s1, 0
	s_max_i32 vcc_lo, vcc_lo, 0
	s_max_i32 vcc_hi, vcc_hi, 0
	s_sub_i32 s1, s1, s0
	s_sub_i32 vcc_hi, vcc_hi, vcc_lo
	s_lshl_b32 s0, s0, 9
	s_lshl_b32 s1, s1, 9
	s_lshl_b32 vcc_lo, vcc_lo, 9
	s_lshl_b32 vcc_hi, vcc_hi, 9
	v_add_u32_e32 v146, s0, v154
	v_add_u32_e32 v147, vcc_lo, v155
	v_mad_i32_i24 v146, v115, s1, v146
	v_mad_i32_i24 v147, v115, vcc_hi, v147
	v_readlane_b32 s0, v244, 56
	v_readlane_b32 s1, v244, 57
	v_readlane_b32 vcc_lo, v244, 58
	v_readlane_b32 vcc_hi, v244, 59
	s_mov_b32 exec_lo, 0x0
	s_mov_b32 exec_hi, 0xffff
	v_mov_b32_e32 v170, s0
	v_mov_b32_e32 v176, s1
	v_mov_b32_e32 v177, vcc_lo
	v_mov_b32_e32 v191, vcc_hi
	s_mov_b64 exec, -1
	s_max_i32 s0, s0, 0
	s_max_i32 s1, s1, 0
	s_max_i32 vcc_lo, vcc_lo, 0
	s_max_i32 vcc_hi, vcc_hi, 0
	s_sub_i32 s1, s1, s0
	s_sub_i32 vcc_hi, vcc_hi, vcc_lo
	s_lshl_b32 s0, s0, 9
	s_lshl_b32 s1, s1, 9
	s_lshl_b32 vcc_lo, vcc_lo, 9
	s_lshl_b32 vcc_hi, vcc_hi, 9
	v_add_u32_e32 v172, s0, v152
	v_add_u32_e32 v173, vcc_lo, v153
	v_mad_i32_i24 v172, v115, s1, v172
	v_mad_i32_i24 v173, v115, vcc_hi, v173
	v_readlane_b32 s0, v244, 60
	v_readlane_b32 s1, v244, 61
	v_readlane_b32 vcc_lo, v244, 62
	v_readlane_b32 vcc_hi, v244, 63
	s_mov_b32 exec_lo, 0x0
	s_mov_b32 exec_hi, 0xffff0000
	v_mov_b32_e32 v170, s0
	v_mov_b32_e32 v176, s1
	v_mov_b32_e32 v177, vcc_lo
	v_mov_b32_e32 v191, vcc_hi
	s_mov_b64 exec, -1
	s_max_i32 s0, s0, 0
	s_max_i32 s1, s1, 0
	s_max_i32 vcc_lo, vcc_lo, 0
	s_max_i32 vcc_hi, vcc_hi, 0
	s_sub_i32 s1, s1, s0
	s_sub_i32 vcc_hi, vcc_hi, vcc_lo
	s_lshl_b32 s0, s0, 9
	s_lshl_b32 s1, s1, 9
	s_lshl_b32 vcc_lo, vcc_lo, 9
	s_lshl_b32 vcc_hi, vcc_hi, 9
	v_add_u32_e32 v174, s0, v154
	v_add_u32_e32 v175, vcc_lo, v155
	v_mad_i32_i24 v174, v115, s1, v174
	v_mad_i32_i24 v175, v115, vcc_hi, v175
	s_branch .Latt_a_done
.Latt_qpf:
	s_cmp_lt_i32 s38, 0
	s_cbranch_scc1 .Latt_a_done
	v_mad_u64_u32 v[132:133], s[0:1], s38, v188, v[100:101]
	global_load_dwordx4 v[196:199], v[132:133], off
	global_load_dwordx4 v[200:203], v[132:133], off offset:64
	global_load_dwordx4 v[204:207], v[132:133], off offset:128
	global_load_dwordx4 v[208:211], v[132:133], off offset:192
	global_load_dwordx4 v[212:215], v[132:133], off offset:256
	global_load_dwordx4 v[216:219], v[132:133], off offset:320
	global_load_dwordx4 v[220:223], v[132:133], off offset:384
	global_load_dwordx4 v[224:227], v[132:133], off offset:448
